# grid barrier rewritten: per-XCD arrival counter elects last workgroup, which writes back L2 and notifies every XCD's GO word directly; everyone polls own XCD's GO word (drops top-level returning atomi
# speedup vs baseline: 1.0370x; 1.0026x over previous
.LBB0_162:
	v_mov_b32_e32 v2, 0x20000
	ds_read_b32 v6, v2
	ds_read_b32 v7, v2 offset:4
	v_readlane_b32 s0, v255, 2
	s_and_b32 s0, s0, 7
	s_lshl_b32 s0, s0, 7
	s_add_i32 s0, s0, 0x3600
	v_mov_b32_e32 v8, s0
	v_mov_b32_e32 v9, 1
	s_mov_b32 s11, 1
	s_mov_b32 s10, 0
	global_atomic_add v10, v8, v9, s[70:71] sc0
	s_waitcnt vmcnt(0) lgkmcnt(0)
	v_mul_lo_u32 v11, v6, s11
	v_add_u32_e32 v10, 1, v10
	v_cmp_eq_u32_e32 vcc, v10, v11
	v_mul_lo_u32 v11, v7, s11
	s_cbranch_vccz .Lxb1_poll
	buffer_wbl2 sc1
	v_mov_b32_e32 v2, 0x3a00
	s_waitcnt vmcnt(0)
	global_atomic_add v2, v9, s[70:71]
	global_atomic_add v2, v9, s[70:71] offset:128
	global_atomic_add v2, v9, s[70:71] offset:256
	global_atomic_add v2, v9, s[70:71] offset:384
	global_atomic_add v2, v9, s[70:71] offset:512
	global_atomic_add v2, v9, s[70:71] offset:640
	global_atomic_add v2, v9, s[70:71] offset:768
	global_atomic_add v2, v9, s[70:71] offset:896
.Lxb1_poll:
	global_load_dword v10, v8, s[70:71] offset:1024 sc1
	s_add_i32 s10, s10, 1
	s_waitcnt vmcnt(0)
	v_cmp_ge_u32_e32 vcc, v10, v11
	s_cbranch_vccnz .Lxb1_done
	s_sleep 1
	s_cmp_lt_u32 s10, 0x8000
	s_cbranch_scc1 .Lxb1_poll
.Lxb1_done:
	buffer_inv sc1
	s_waitcnt vmcnt(0)

.LBB0_203:
	s_waitcnt vmcnt(0)
	s_barrier
	s_mov_b64 s[4:5], exec
	v_readlane_b32 s0, v255, 3
	s_mov_b32 s6, s68
	v_readlane_b32 s1, v255, 4
	v_writelane_b32 v255, s6, 10
	s_and_b64 s[0:1], s[4:5], s[0:1]
	s_nop 0
	v_writelane_b32 v255, s7, 11
	s_mov_b64 exec, s[0:1]
	s_cbranch_execz .LBB0_255
	v_mov_b32_e32 v2, 0x20000
	ds_read_b32 v6, v2
	ds_read_b32 v7, v2 offset:4
	v_readlane_b32 s0, v255, 2
	s_and_b32 s0, s0, 7
	s_lshl_b32 s0, s0, 7
	s_add_i32 s0, s0, 0x3600
	v_mov_b32_e32 v8, s0
	v_mov_b32_e32 v9, 1
	s_mov_b32 s11, 2
	s_mov_b32 s10, 0
	global_atomic_add v10, v8, v9, s[70:71] sc0
	s_waitcnt vmcnt(0) lgkmcnt(0)
	v_mul_lo_u32 v11, v6, s11
	v_add_u32_e32 v10, 1, v10
	v_cmp_eq_u32_e32 vcc, v10, v11
	v_mul_lo_u32 v11, v7, s11
	s_cbranch_vccz .Lxb2_poll
	buffer_wbl2 sc1
	v_mov_b32_e32 v2, 0x3a00
	s_waitcnt vmcnt(0)
	global_atomic_add v2, v9, s[70:71]
	global_atomic_add v2, v9, s[70:71] offset:128
	global_atomic_add v2, v9, s[70:71] offset:256
	global_atomic_add v2, v9, s[70:71] offset:384
	global_atomic_add v2, v9, s[70:71] offset:512
	global_atomic_add v2, v9, s[70:71] offset:640
	global_atomic_add v2, v9, s[70:71] offset:768
	global_atomic_add v2, v9, s[70:71] offset:896

.LBB0_297:
	s_waitcnt vmcnt(0)
	s_waitcnt vmcnt(0)
	s_barrier
	s_mov_b64 s[4:5], exec
	v_readlane_b32 s0, v255, 3
	v_readlane_b32 s1, v255, 4
	s_and_b64 s[0:1], s[4:5], s[0:1]
	s_mov_b64 exec, s[0:1]
	s_cbranch_execz .LBB0_349
	v_mov_b32_e32 v2, 0x20000
	ds_read_b32 v6, v2
	ds_read_b32 v7, v2 offset:4
	v_readlane_b32 s0, v255, 2
	s_and_b32 s0, s0, 7
	s_lshl_b32 s0, s0, 7
	s_add_i32 s0, s0, 0x3600
	v_mov_b32_e32 v8, s0
	v_mov_b32_e32 v9, 1
	s_mov_b32 s11, 3
	s_mov_b32 s10, 0
	global_atomic_add v10, v8, v9, s[70:71] sc0
	s_waitcnt vmcnt(0) lgkmcnt(0)
	v_mul_lo_u32 v11, v6, s11
	v_add_u32_e32 v10, 1, v10
	v_cmp_eq_u32_e32 vcc, v10, v11
	v_mul_lo_u32 v11, v7, s11
	s_cbranch_vccz .Lxb3_poll
	buffer_wbl2 sc1
	v_mov_b32_e32 v2, 0x3a00
	s_waitcnt vmcnt(0)
	global_atomic_add v2, v9, s[70:71]
	global_atomic_add v2, v9, s[70:71] offset:128
	global_atomic_add v2, v9, s[70:71] offset:256
	global_atomic_add v2, v9, s[70:71] offset:384
	global_atomic_add v2, v9, s[70:71] offset:512
	global_atomic_add v2, v9, s[70:71] offset:640
	global_atomic_add v2, v9, s[70:71] offset:768
	global_atomic_add v2, v9, s[70:71] offset:896

.LBB0_405:
	s_waitcnt vmcnt(0)
	s_barrier
	s_mov_b64 s[4:5], exec
	v_readlane_b32 s0, v255, 3
	v_readlane_b32 s1, v255, 4
	s_and_b64 s[0:1], s[4:5], s[0:1]
	s_mov_b64 exec, s[0:1]
	s_cbranch_execz .LBB0_457
	v_mov_b32_e32 v2, 0x20000
	ds_read_b32 v6, v2
	ds_read_b32 v7, v2 offset:4
	v_readlane_b32 s0, v255, 2
	s_and_b32 s0, s0, 7
	s_lshl_b32 s0, s0, 7
	s_add_i32 s0, s0, 0x3600
	v_mov_b32_e32 v8, s0
	v_mov_b32_e32 v9, 1
	s_mov_b32 s11, 4
	s_mov_b32 s10, 0
	global_atomic_add v10, v8, v9, s[70:71] sc0
	s_waitcnt vmcnt(0) lgkmcnt(0)
	v_mul_lo_u32 v11, v6, s11
	v_add_u32_e32 v10, 1, v10
	v_cmp_eq_u32_e32 vcc, v10, v11
	v_mul_lo_u32 v11, v7, s11
	s_cbranch_vccz .Lxb4_poll
	buffer_wbl2 sc1
	v_mov_b32_e32 v2, 0x3a00
	s_waitcnt vmcnt(0)
	global_atomic_add v2, v9, s[70:71]
	global_atomic_add v2, v9, s[70:71] offset:128
	global_atomic_add v2, v9, s[70:71] offset:256
	global_atomic_add v2, v9, s[70:71] offset:384
	global_atomic_add v2, v9, s[70:71] offset:512
	global_atomic_add v2, v9, s[70:71] offset:640
	global_atomic_add v2, v9, s[70:71] offset:768
	global_atomic_add v2, v9, s[70:71] offset:896

.LBB0_605:
	s_waitcnt vmcnt(0)
	s_barrier
	s_mov_b64 s[4:5], exec
	v_readlane_b32 s0, v255, 3
	v_readlane_b32 s1, v255, 4
	s_and_b64 s[0:1], s[4:5], s[0:1]
	s_mov_b64 exec, s[0:1]
	s_cbranch_execz .LBB0_657
	v_mov_b32_e32 v2, 0x20000
	ds_read_b32 v6, v2
	ds_read_b32 v7, v2 offset:4
	v_readlane_b32 s0, v255, 2
	s_and_b32 s0, s0, 7
	s_lshl_b32 s0, s0, 7
	s_add_i32 s0, s0, 0x3600
	v_mov_b32_e32 v8, s0
	v_mov_b32_e32 v9, 1
	s_mov_b32 s11, 5
	s_mov_b32 s10, 0
	global_atomic_add v10, v8, v9, s[70:71] sc0
	s_waitcnt vmcnt(0) lgkmcnt(0)
	v_mul_lo_u32 v11, v6, s11
	v_add_u32_e32 v10, 1, v10
	v_cmp_eq_u32_e32 vcc, v10, v11
	v_mul_lo_u32 v11, v7, s11
	s_cbranch_vccz .Lxb5_poll
	buffer_wbl2 sc1
	v_mov_b32_e32 v2, 0x3a00
	s_waitcnt vmcnt(0)
	global_atomic_add v2, v9, s[70:71]
	global_atomic_add v2, v9, s[70:71] offset:128
	global_atomic_add v2, v9, s[70:71] offset:256
	global_atomic_add v2, v9, s[70:71] offset:384
	global_atomic_add v2, v9, s[70:71] offset:512
	global_atomic_add v2, v9, s[70:71] offset:640
	global_atomic_add v2, v9, s[70:71] offset:768
	global_atomic_add v2, v9, s[70:71] offset:896

.LBB0_686:
	s_waitcnt vmcnt(0)
	s_waitcnt vmcnt(0)
	s_barrier
	s_mov_b64 s[4:5], exec
	v_readlane_b32 s0, v255, 3
	v_readlane_b32 s1, v255, 4
	s_and_b64 s[0:1], s[4:5], s[0:1]
	s_mov_b64 exec, s[0:1]
	s_cbranch_execz .LBB0_738
	v_mov_b32_e32 v2, 0x20000
	ds_read_b32 v6, v2
	ds_read_b32 v7, v2 offset:4
	v_readlane_b32 s0, v255, 2
	s_and_b32 s0, s0, 7
	s_lshl_b32 s0, s0, 7
	s_add_i32 s0, s0, 0x3600
	v_mov_b32_e32 v8, s0
	v_mov_b32_e32 v9, 1
	s_mov_b32 s11, 6
	s_mov_b32 s10, 0
	global_atomic_add v10, v8, v9, s[70:71] sc0
	s_waitcnt vmcnt(0) lgkmcnt(0)
	v_mul_lo_u32 v11, v6, s11
	v_add_u32_e32 v10, 1, v10
	v_cmp_eq_u32_e32 vcc, v10, v11
	v_mul_lo_u32 v11, v7, s11
	s_cbranch_vccz .Lxb6_poll
	buffer_wbl2 sc1
	v_mov_b32_e32 v2, 0x3a00
	s_waitcnt vmcnt(0)
	global_atomic_add v2, v9, s[70:71]
	global_atomic_add v2, v9, s[70:71] offset:128
	global_atomic_add v2, v9, s[70:71] offset:256
	global_atomic_add v2, v9, s[70:71] offset:384
	global_atomic_add v2, v9, s[70:71] offset:512
	global_atomic_add v2, v9, s[70:71] offset:640
	global_atomic_add v2, v9, s[70:71] offset:768
	global_atomic_add v2, v9, s[70:71] offset:896

.Lp6_nosample:
.LBB0_755:
	s_waitcnt vmcnt(0)
	s_barrier
	s_mov_b64 s[6:7], exec
	v_readlane_b32 s0, v255, 3
	v_readlane_b32 s1, v255, 4
	s_and_b64 s[0:1], s[6:7], s[0:1]
	s_mov_b64 exec, s[0:1]
	s_cbranch_execz .LBB0_807
	v_mov_b32_e32 v2, 0x20000
	ds_read_b32 v6, v2
	ds_read_b32 v7, v2 offset:4
	v_readlane_b32 s0, v255, 2
	s_and_b32 s0, s0, 7
	s_lshl_b32 s0, s0, 7
	s_add_i32 s0, s0, 0x3600
	v_mov_b32_e32 v8, s0
	v_mov_b32_e32 v9, 1
	s_mov_b32 s11, 7
	s_mov_b32 s10, 0
	global_atomic_add v10, v8, v9, s[70:71] sc0
	s_waitcnt vmcnt(0) lgkmcnt(0)
	v_mul_lo_u32 v11, v6, s11
	v_add_u32_e32 v10, 1, v10
	v_cmp_eq_u32_e32 vcc, v10, v11
	v_mul_lo_u32 v11, v7, s11
	s_cbranch_vccz .Lxb7_poll
	buffer_wbl2 sc1
	v_mov_b32_e32 v2, 0x3a00
	s_waitcnt vmcnt(0)
	global_atomic_add v2, v9, s[70:71]
	global_atomic_add v2, v9, s[70:71] offset:128
	global_atomic_add v2, v9, s[70:71] offset:256
	global_atomic_add v2, v9, s[70:71] offset:384
	global_atomic_add v2, v9, s[70:71] offset:512
	global_atomic_add v2, v9, s[70:71] offset:640
	global_atomic_add v2, v9, s[70:71] offset:768
	global_atomic_add v2, v9, s[70:71] offset:896

.LBB0_864:
	s_waitcnt vmcnt(0)
	s_barrier
	s_mov_b64 s[6:7], exec
	v_readlane_b32 s0, v255, 3
	v_readlane_b32 s1, v255, 4
	v_readlane_b32 s82, v255, 6
	s_and_b64 s[0:1], s[6:7], s[0:1]
	v_readlane_b32 s83, v255, 7
	s_mov_b64 exec, s[0:1]
	s_cbranch_execz .LBB0_916
	v_mov_b32_e32 v2, 0x20000
	ds_read_b32 v6, v2
	ds_read_b32 v7, v2 offset:4
	v_readlane_b32 s0, v255, 2
	s_and_b32 s0, s0, 7
	s_lshl_b32 s0, s0, 7
	s_add_i32 s0, s0, 0x3600
	v_mov_b32_e32 v8, s0
	v_mov_b32_e32 v9, 1
	s_mov_b32 s11, 8
	s_mov_b32 s10, 0
	global_atomic_add v10, v8, v9, s[70:71] sc0
	s_waitcnt vmcnt(0) lgkmcnt(0)
	v_mul_lo_u32 v11, v6, s11
	v_add_u32_e32 v10, 1, v10
	v_cmp_eq_u32_e32 vcc, v10, v11
	v_mul_lo_u32 v11, v7, s11
	s_cbranch_vccz .Lxb8_poll
	buffer_wbl2 sc1
	v_mov_b32_e32 v2, 0x3a00
	s_waitcnt vmcnt(0)
	global_atomic_add v2, v9, s[70:71]
	global_atomic_add v2, v9, s[70:71] offset:128
	global_atomic_add v2, v9, s[70:71] offset:256
	global_atomic_add v2, v9, s[70:71] offset:384
	global_atomic_add v2, v9, s[70:71] offset:512
	global_atomic_add v2, v9, s[70:71] offset:640
	global_atomic_add v2, v9, s[70:71] offset:768
	global_atomic_add v2, v9, s[70:71] offset:896

.LBB0_953:
	s_waitcnt vmcnt(0)
	s_waitcnt vmcnt(0)
	s_barrier
	s_mov_b64 s[2:3], exec
	v_readlane_b32 s0, v255, 3
	v_readlane_b32 s1, v255, 4
	s_and_b64 s[0:1], s[2:3], s[0:1]
	s_mov_b64 exec, s[0:1]
	s_cbranch_execz .LBB0_1005
	v_mov_b32_e32 v2, 0x20000
	ds_read_b32 v6, v2
	ds_read_b32 v7, v2 offset:4
	v_readlane_b32 s0, v255, 2
	s_and_b32 s0, s0, 7
	s_lshl_b32 s0, s0, 7
	s_add_i32 s0, s0, 0x3600
	v_mov_b32_e32 v8, s0
	v_mov_b32_e32 v9, 1
	s_mov_b32 s11, 9
	s_mov_b32 s10, 0
	global_atomic_add v10, v8, v9, s[70:71] sc0
	s_waitcnt vmcnt(0) lgkmcnt(0)
	v_mul_lo_u32 v11, v6, s11
	v_add_u32_e32 v10, 1, v10
	v_cmp_eq_u32_e32 vcc, v10, v11
	v_mul_lo_u32 v11, v7, s11
	s_cbranch_vccz .Lxb9_poll
	buffer_wbl2 sc1
	v_mov_b32_e32 v2, 0x3a00
	s_waitcnt vmcnt(0)
	global_atomic_add v2, v9, s[70:71]
	global_atomic_add v2, v9, s[70:71] offset:128
	global_atomic_add v2, v9, s[70:71] offset:256
	global_atomic_add v2, v9, s[70:71] offset:384
	global_atomic_add v2, v9, s[70:71] offset:512
	global_atomic_add v2, v9, s[70:71] offset:640
	global_atomic_add v2, v9, s[70:71] offset:768
	global_atomic_add v2, v9, s[70:71] offset:896
